# plus: FoX tile-skip bound loads batched; first-tile QK blocks of both unit prologues issue all LDS fragment reads up front
# speedup vs baseline: 1.0334x; 1.0058x over previous
.LBB0_636:
	s_or_b64 exec, exec, s[4:5]
	v_mov_b32_e32 v0, s2
	s_waitcnt lgkmcnt(0)
	s_barrier
	ds_read_b32 v0, v0
	s_mov_b64 s[4:5], -1
	s_waitcnt lgkmcnt(0)
	v_readfirstlane_b32 s3, v0
	s_cmpk_gt_i32 s3, 0x7ff
	s_cbranch_scc1 .LBB0_631
	s_bfe_u32 s34, s3, 0x40006
	s_xor_b32 s39, s34, 15
	s_and_b32 s38, s3, 63
	s_lshl_b32 s35, s39, 2
	s_cmpk_gt_i32 s3, 0x3ff
	s_cbranch_scc0 .LBB0_713
	s_mov_b32 s4, s33
	v_mbcnt_lo_u32_b32 v18, -1, 0
	v_mbcnt_hi_u32_b32 v18, -1, v18
	s_lshl_b32 s10, s39, 8
	v_lshl_or_b32 v19, s4, 6, v18
	s_lshr_b32 s11, s38, 3
	v_readfirstlane_b32 s4, v19
	s_ashr_i32 s5, s4, 1
	s_and_b32 s40, s5, 0xffffffe0
	s_add_i32 s40, s40, s10
	s_and_b32 s14, s3, 7
	s_lshl_b32 s52, s11, 12
	s_ashr_i32 s5, s40, 31
	s_add_u32 s6, s40, s52
	v_and_b32_e32 v20, 31, v18
	s_addc_u32 s5, s5, 0
	v_or_b32_e32 v0, s6, v20
	v_mov_b32_e32 v1, s5
	v_lshlrev_b64 v[134:135], 10, v[0:1]
	v_bfe_u32 v21, v18, 5, 1
	v_lshl_add_u64 v[0:1], s[50:51], 0, v[134:135]
	s_lshl_b32 s96, s14, 7
	v_lshl_add_u64 v[0:1], v[0:1], 0, s[96:97]
	v_lshlrev_b32_e32 v30, 4, v21
	v_mov_b32_e32 v31, v13
	v_lshl_add_u64 v[14:15], v[0:1], 0, v[30:31]
	global_load_dwordx4 v[0:3], v[14:15], off
	global_load_dwordx4 v[4:7], v[14:15], off offset:32
	global_load_dwordx4 v[8:11], v[14:15], off offset:64
	global_load_dwordx4 v[110:113], v[14:15], off offset:96
	s_add_i32 s41, s35, 4
	v_and_b32_e32 v22, 63, v18
	s_cmp_gt_u32 s4, 63
	s_cbranch_scc1 .LBB0_644
	v_cmp_gt_u32_e32 vcc, s41, v22
	s_mov_b64 s[4:5], 0
	s_and_saveexec_b64 s[6:7], vcc
	s_cbranch_execz .LBB0_641
	s_lshl_b32 s4, s38, 4
	v_mov_b32_e32 v12, s4
	v_readlane_b32 s4, v253, 34
	v_readlane_b32 s5, v253, 35
	s_mov_b32 s12, 0xf800000
	s_nop 3
	global_load_dwordx4 v[14:17], v12, s[4:5]
	v_readlane_b32 s16, v253, 44
	v_readlane_b32 s17, v253, 45
	s_lshl_b32 s26, s38, 14
	s_nop 3
	s_add_u32 s16, s16, s26
	s_addc_u32 s17, s17, 0
	s_lshl_b32 s26, s10, 2
	v_mov_b32_e32 v190, s26
	global_load_dword v190, v190, s[16:17]
	v_lshlrev_b32_e32 v191, 8, v22
	global_load_dword v191, v191, s[16:17] offset:252
	s_waitcnt vmcnt(2)
	v_add_f32_e32 v12, v16, v17
	v_cmp_gt_f32_e32 vcc, s12, v12
	v_mul_f32_e32 v16, 0x4f800000, v12
	v_add_f32_e32 v14, v14, v15
	v_cndmask_b32_e32 v12, v12, v16, vcc
	v_sqrt_f32_e32 v16, v12
	v_mul_f32_e32 v15, 0x4f800000, v14
	v_add_u32_e32 v17, -1, v16
	v_fma_f32 v23, -v17, v16, v12
	v_cmp_ge_f32_e64 s[4:5], 0, v23
	v_add_u32_e32 v23, 1, v16
	s_nop 0
	v_cndmask_b32_e64 v17, v16, v17, s[4:5]
	v_fma_f32 v16, -v23, v16, v12
	v_cmp_lt_f32_e64 s[4:5], 0, v16
	s_nop 1
	v_cndmask_b32_e64 v16, v17, v23, s[4:5]
	v_mul_f32_e32 v17, 0x37800000, v16
	v_mov_b32_e32 v23, 0x260
	v_cndmask_b32_e32 v16, v16, v17, vcc
	v_cmp_class_f32_e32 vcc, v12, v23
	s_nop 1
	v_cndmask_b32_e32 v12, v16, v12, vcc
	v_cmp_gt_f32_e32 vcc, s12, v14
	v_readlane_b32 s12, v253, 44
	v_readlane_b32 s13, v253, 45
	v_cndmask_b32_e32 v14, v14, v15, vcc
	v_sqrt_f32_e32 v15, v14
	s_nop 0
	v_add_u32_e32 v16, -1, v15
	v_fma_f32 v17, -v16, v15, v14
	v_cmp_ge_f32_e64 s[4:5], 0, v17
	v_add_u32_e32 v17, 1, v15
	s_nop 0
	v_cndmask_b32_e64 v16, v15, v16, s[4:5]
	v_fma_f32 v15, -v17, v15, v14
	v_cmp_lt_f32_e64 s[4:5], 0, v15
	s_nop 1
	v_cndmask_b32_e64 v15, v16, v17, s[4:5]
	s_lshl_b32 s4, s38, 14
	v_mul_f32_e32 v16, 0x37800000, v15
	s_add_u32 s4, s12, s4
	v_cndmask_b32_e32 v15, v15, v16, vcc
	v_cmp_class_f32_e32 vcc, v14, v23
	s_addc_u32 s5, s13, 0
	s_lshl_b32 s10, s10, 2
	v_cndmask_b32_e32 v14, v15, v14, vcc
	v_mov_b32_e32 v15, s10
	v_mul_f32_e32 v12, v12, v14
	s_mov_b32 s10, 0x3f828f5c
	v_fma_f32 v12, v12, s10, 1.0
	s_waitcnt vmcnt(1)
	v_mov_b32_e32 v15, v190
	v_fmac_f32_e32 v15, 2.0, v12
	s_mov_b32 s4, 0xc2800000
	s_waitcnt vmcnt(0)
	v_sub_f32_e32 v12, v15, v191
	v_cmp_le_f32_e32 vcc, s4, v12
	s_and_b64 s[4:5], vcc, exec

.LBB0_650:
	s_or_b64 exec, exec, s[54:55]
	s_waitcnt vmcnt(0)
	ds_write_b128 v153, v[114:117] offset:13312
	s_and_saveexec_b64 s[52:53], s[6:7]
	ds_write_b32 v154, v152 offset:43264
	s_or_b64 exec, exec, s[52:53]
	s_and_b32 s55, s10, 1
	s_lshl_b32 s11, s55, 8
	s_add_i32 s52, s11, 0
	s_mul_i32 s16, s55, 0x3300
	v_add_u32_e32 v26, s52, v30
	s_add_i32 s52, s52, s16
	v_mov_b32_e32 v14, s52
	s_movk_i32 s16, 0x90
	v_mad_u32_u24 v14, v20, s16, v14
	v_add_u32_e32 v163, v14, v30
	s_waitcnt lgkmcnt(0)
	s_barrier
	ds_read_b128 v[190:193], v163
	ds_read_b128 v[46:49], v26 offset:43008
	ds_read_b128 v[50:53], v26 offset:43040
	ds_read_b128 v[54:57], v26 offset:43072
	ds_read_b128 v[58:61], v26 offset:43104
	ds_read_b128 v[198:201], v163 offset:4608
	ds_read_b128 v[62:65], v26 offset:43136
	ds_read_b128 v[66:69], v26 offset:43168
	ds_read_b128 v[70:73], v26 offset:43200
	ds_read_b128 v[74:77], v26 offset:43232
	ds_read_b128 v[194:197], v163 offset:32
	ds_read_b128 v[202:205], v163 offset:4640
	ds_read_b128 v[206:209], v163 offset:64
	ds_read_b128 v[210:213], v163 offset:4672
	ds_read_b128 v[214:217], v163 offset:96
	s_waitcnt lgkmcnt(10)
	v_mfma_f32_32x32x16_bf16 v[46:61], v[190:193], v[0:3], v[46:61]
	ds_read_b128 v[222:225], v163 offset:4704
	s_lshl_b32 s16, s10, 6
	s_or_b32 s17, s16, 63
	v_lshlrev_b32_e32 v156, 2, v21
	s_cmp_le_i32 s17, s40
	v_or_b32_e32 v157, s40, v20
	s_waitcnt lgkmcnt(5)
	v_mfma_f32_32x32x16_bf16 v[46:61], v[194:197], v[4:7], v[46:61]
	s_waitcnt lgkmcnt(6)
	v_mfma_f32_32x32x16_bf16 v[62:77], v[198:201], v[0:3], v[62:77]
	s_waitcnt lgkmcnt(4)
	v_mfma_f32_32x32x16_bf16 v[62:77], v[202:205], v[4:7], v[62:77]
	s_waitcnt lgkmcnt(3)
	v_mfma_f32_32x32x16_bf16 v[46:61], v[206:209], v[8:11], v[46:61]
	s_waitcnt lgkmcnt(2)
	v_mfma_f32_32x32x16_bf16 v[62:77], v[210:213], v[8:11], v[62:77]
	s_waitcnt lgkmcnt(1)
	v_mfma_f32_32x32x16_bf16 v[46:61], v[214:217], v[110:113], v[46:61]
	s_waitcnt lgkmcnt(0)
	v_mfma_f32_32x32x16_bf16 v[62:77], v[222:225], v[110:113], v[62:77]
	s_cbranch_scc1 .LBB0_654
	v_or_b32_e32 v14, s16, v156
	v_or_b32_e32 v15, 32, v14
	v_cmp_le_i32_e32 vcc, v15, v157
	v_or_b32_e32 v15, 33, v14
	s_nop 6
	v_cndmask_b32_e32 v62, v220, v62, vcc
	v_cmp_lt_i32_e32 vcc, v14, v157
	s_nop 1
	v_cndmask_b32_e32 v47, v220, v47, vcc
	v_cmp_le_i32_e32 vcc, v14, v157
	s_nop 1
	v_cndmask_b32_e32 v46, v220, v46, vcc
	v_cmp_le_i32_e32 vcc, v15, v157
	v_or_b32_e32 v15, 2, v14
	s_nop 0
	v_cndmask_b32_e32 v63, v220, v63, vcc
	v_cmp_le_i32_e32 vcc, v15, v157
	v_or_b32_e32 v15, 34, v14
	s_nop 0
	v_cndmask_b32_e32 v48, v220, v48, vcc
	v_cmp_le_i32_e32 vcc, v15, v157
	v_or_b32_e32 v15, 3, v14
	s_nop 0
	v_cndmask_b32_e32 v64, v220, v64, vcc
	v_cmp_le_i32_e32 vcc, v15, v157
	v_or_b32_e32 v15, 35, v14
	s_nop 0
	v_cndmask_b32_e32 v49, v220, v49, vcc
	v_cmp_le_i32_e32 vcc, v15, v157
	v_or_b32_e32 v15, 8, v14
	s_nop 0
	v_cndmask_b32_e32 v65, v220, v65, vcc
	v_cmp_le_i32_e32 vcc, v15, v157
	v_or_b32_e32 v15, 40, v14
	s_nop 0
	v_cndmask_b32_e32 v50, v220, v50, vcc
	v_cmp_le_i32_e32 vcc, v15, v157
	v_or_b32_e32 v15, 9, v14
	s_nop 0
	v_cndmask_b32_e32 v66, v220, v66, vcc
	v_cmp_le_i32_e32 vcc, v15, v157
	v_or_b32_e32 v15, 41, v14
	s_nop 0
	v_cndmask_b32_e32 v51, v220, v51, vcc
	v_cmp_le_i32_e32 vcc, v15, v157
	v_or_b32_e32 v15, 10, v14
	s_nop 0
	v_cndmask_b32_e32 v67, v220, v67, vcc
	v_cmp_le_i32_e32 vcc, v15, v157
	v_or_b32_e32 v15, 42, v14
	s_nop 0
	v_cndmask_b32_e32 v52, v220, v52, vcc
	v_cmp_le_i32_e32 vcc, v15, v157
	v_or_b32_e32 v15, 11, v14
	s_nop 0
	v_cndmask_b32_e32 v68, v220, v68, vcc
	v_cmp_le_i32_e32 vcc, v15, v157
	v_or_b32_e32 v15, 43, v14
	s_nop 0
	v_cndmask_b32_e32 v53, v220, v53, vcc
	v_cmp_le_i32_e32 vcc, v15, v157
	v_or_b32_e32 v15, 16, v14
	s_nop 0
	v_cndmask_b32_e32 v69, v220, v69, vcc
	v_cmp_le_i32_e32 vcc, v15, v157
	v_or_b32_e32 v15, 48, v14
	s_nop 0
	v_cndmask_b32_e32 v54, v220, v54, vcc
	v_cmp_le_i32_e32 vcc, v15, v157
	v_or_b32_e32 v15, 17, v14
	s_nop 0
	v_cndmask_b32_e32 v70, v220, v70, vcc
	v_cmp_le_i32_e32 vcc, v15, v157
	v_or_b32_e32 v15, 49, v14
	s_nop 0
	v_cndmask_b32_e32 v55, v220, v55, vcc
	v_cmp_le_i32_e32 vcc, v15, v157
	v_or_b32_e32 v15, 18, v14
	s_nop 0
	v_cndmask_b32_e32 v71, v220, v71, vcc
	v_cmp_le_i32_e32 vcc, v15, v157
	v_or_b32_e32 v15, 50, v14
	s_nop 0
	v_cndmask_b32_e32 v56, v220, v56, vcc
	v_cmp_le_i32_e32 vcc, v15, v157
	v_or_b32_e32 v15, 19, v14
	s_nop 0
	v_cndmask_b32_e32 v72, v220, v72, vcc
	v_cmp_le_i32_e32 vcc, v15, v157
	v_or_b32_e32 v15, 51, v14
	s_nop 0
	v_cndmask_b32_e32 v57, v220, v57, vcc
	v_cmp_le_i32_e32 vcc, v15, v157
	v_or_b32_e32 v15, 24, v14
	s_nop 0
	v_cndmask_b32_e32 v73, v220, v73, vcc
	v_cmp_le_i32_e32 vcc, v15, v157
	v_or_b32_e32 v15, 56, v14
	s_nop 0
	v_cndmask_b32_e32 v58, v220, v58, vcc
	v_cmp_le_i32_e32 vcc, v15, v157
	v_or_b32_e32 v15, 25, v14
	s_nop 0
	v_cndmask_b32_e32 v74, v220, v74, vcc
	v_cmp_le_i32_e32 vcc, v15, v157
	v_or_b32_e32 v15, 57, v14
	s_nop 0
	v_cndmask_b32_e32 v59, v220, v59, vcc
	v_cmp_le_i32_e32 vcc, v15, v157
	v_or_b32_e32 v15, 26, v14
	s_nop 0
	v_cndmask_b32_e32 v75, v220, v75, vcc
	v_cmp_le_i32_e32 vcc, v15, v157
	v_or_b32_e32 v15, 58, v14
	s_nop 0
	v_cndmask_b32_e32 v60, v220, v60, vcc
	v_cmp_le_i32_e32 vcc, v15, v157
	v_or_b32_e32 v15, 27, v14
	v_or_b32_e32 v14, 59, v14
	v_cndmask_b32_e32 v76, v220, v76, vcc
	v_cmp_le_i32_e32 vcc, v15, v157
	s_nop 1
	v_cndmask_b32_e32 v61, v220, v61, vcc
	v_cmp_le_i32_e32 vcc, v14, v157
	s_nop 1
	v_cndmask_b32_e32 v77, v220, v77, vcc

.LBB0_720:
	s_or_b64 exec, exec, s[10:11]
	s_waitcnt vmcnt(0)
	ds_write_b128 v158, v[126:129] offset:13312
	s_and_saveexec_b64 s[4:5], s[6:7]
	ds_write_b128 v16, v[122:125] offset:13440
	s_or_b64 exec, exec, s[4:5]
	v_lshlrev_b32_e32 v17, 3, v28
	v_lshlrev_b32_e32 v16, 1, v28
	v_and_b32_e32 v17, 24, v17
	v_and_or_b32 v16, v16, 32, v17
	v_lshlrev_b32_e32 v160, 2, v29
	v_lshrrev_b32_e32 v17, 2, v28
	v_and_or_b32 v17, v17, 3, v160
	v_lshl_or_b32 v161, v17, 6, v16
	v_mad_u32_u24 v16, v27, s16, 0
	v_add_u32_e32 v162, v16, v20
	s_waitcnt lgkmcnt(0)
	s_barrier
	ds_read_b128 v[190:193], v162 offset:6656
	ds_read_b128 v[194:197], v162
	ds_read_b128 v[198:201], v162 offset:32
	ds_read_b128 v[202:205], v162 offset:6688
	ds_read_b128 v[206:209], v162 offset:64
	ds_read_b128 v[210:213], v162 offset:6720
	ds_read_b128 v[214:217], v162 offset:96
	ds_read_b128 v[222:225], v162 offset:6752
	ds_read_b128 v[226:229], v162 offset:128
	ds_read_b128 v[230:233], v162 offset:6784
	ds_read_b128 v[16:19], v162 offset:160
	ds_read_b128 v[22:25], v162 offset:6816
	s_waitcnt lgkmcnt(11)
	v_mfma_f32_32x32x16_bf16 v[62:77], v[190:193], v[0:3], 0
	s_add_i32 s35, s35, 4
	s_mov_b32 s52, 0
	s_cmp_eq_u32 s34, 15
	v_add_u32_e32 v163, v14, v15
	v_add_u32_e32 v150, v21, v26
	s_waitcnt lgkmcnt(10)
	v_mfma_f32_32x32x16_bf16 v[46:61], v[194:197], v[0:3], 0
	s_waitcnt lgkmcnt(9)
	v_mfma_f32_32x32x16_bf16 v[46:61], v[198:201], v[4:7], v[46:61]
	s_waitcnt lgkmcnt(8)
	v_mfma_f32_32x32x16_bf16 v[62:77], v[202:205], v[4:7], v[62:77]
	s_waitcnt lgkmcnt(7)
	v_mfma_f32_32x32x16_bf16 v[46:61], v[206:209], v[8:11], v[46:61]
	s_waitcnt lgkmcnt(6)
	v_mfma_f32_32x32x16_bf16 v[62:77], v[210:213], v[8:11], v[62:77]
	s_waitcnt lgkmcnt(5)
	v_mfma_f32_32x32x16_bf16 v[46:61], v[214:217], v[110:113], v[46:61]
	s_waitcnt lgkmcnt(4)
	v_mfma_f32_32x32x16_bf16 v[62:77], v[222:225], v[110:113], v[62:77]
	s_waitcnt lgkmcnt(3)
	v_mfma_f32_32x32x16_bf16 v[46:61], v[226:229], v[114:117], v[46:61]
	s_waitcnt lgkmcnt(2)
	v_mfma_f32_32x32x16_bf16 v[62:77], v[230:233], v[114:117], v[62:77]
	s_waitcnt lgkmcnt(0)
	s_barrier
	v_mfma_f32_32x32x16_bf16 v[46:61], v[16:19], v[118:121], v[46:61]
	v_mfma_f32_32x32x16_bf16 v[62:77], v[22:25], v[118:121], v[62:77]
	v_mov_b32_e32 v14, 0
	v_mov_b32_e32 v15, 0
	v_mov_b32_e32 v16, 0
	v_mov_b32_e32 v17, 0
	v_mov_b32_e32 v18, 0
	v_mov_b32_e32 v19, 0
	v_mov_b32_e32 v20, 0
	v_mov_b32_e32 v21, 0
	v_mov_b32_e32 v22, 0
	v_mov_b32_e32 v23, 0
	v_mov_b32_e32 v24, 0
	v_mov_b32_e32 v25, 0
	v_mov_b32_e32 v26, 0
	v_mov_b32_e32 v27, 0
	v_mov_b32_e32 v28, 0
	v_mov_b32_e32 v29, 0
	v_mov_b32_e32 v30, 0
	v_mov_b32_e32 v31, 0
	v_mov_b32_e32 v32, 0
	v_mov_b32_e32 v33, 0
	v_mov_b32_e32 v34, 0
	v_mov_b32_e32 v35, 0
	v_mov_b32_e32 v36, 0
	v_mov_b32_e32 v37, 0
	v_mov_b32_e32 v38, 0
	v_mov_b32_e32 v39, 0
	v_mov_b32_e32 v40, 0
	v_mov_b32_e32 v41, 0
	v_mov_b32_e32 v42, 0
	v_mov_b32_e32 v43, 0
	v_mov_b32_e32 v44, 0
	v_mov_b32_e32 v45, 0
	v_mov_b32_e32 v165, 0
	s_and_b32 s4, s3, 56
	s_lshl_b32 s4, s4, 19
	s_or_b32 s4, s4, s12
	s_add_u32 s54, s22, s4
	s_addc_u32 s55, s23, 0
	s_add_u32 s54, s54, 0x15a20000
	s_addc_u32 s55, s55, 0
	s_add_u32 s56, s22, s96
	s_addc_u32 s57, s23, 0
	s_add_u32 s56, s56, 0x12802000
	s_addc_u32 s57, s57, 0
	v_lshlrev_b32_e32 v226, 1, v148
	v_lshlrev_b32_e32 v227, 1, v12
	v_add_u32_e32 v227, 0x1ff0000, v227
	v_lshlrev_b32_e32 v228, 1, v150
	global_load_dwordx4 v[126:129], v226, s[54:55]
	s_and_saveexec_b64 s[4:5], s[6:7]
	s_cbranch_execz .Lm3_nokrp
	global_load_dwordx4 v[122:125], v228, s[56:57]
